# np16 + nt cache policy on the read-once f32 activation loads of the modulate phase
# speedup vs baseline: 1.0246x; 1.0088x over previous
.LBB0_139:
	s_add_i32 s6, s33, s41
	v_add_u32_e32 v8, s33, v10
	s_lshr_b32 s6, s6, 12
	v_ashrrev_i32_e32 v9, 31, v8
	v_cmp_gt_i32_e32 vcc, s42, v8
	v_add_u32_e32 v17, 0xffffe000, v8
	v_add_u32_e32 v16, 4, v8
	v_add_u32_e32 v52, 0xffffe004, v8
	v_add_u32_e32 v18, 8, v8
	v_add_u32_e32 v20, 12, v8
	v_add_u32_e32 v22, 16, v8
	v_add_u32_e32 v24, 20, v8
	v_add_u32_e32 v26, 24, v8
	v_add_u32_e32 v28, 28, v8
	v_add_u32_e32 v30, 32, v8
	v_add_u32_e32 v32, 36, v8
	v_add_u32_e32 v34, 40, v8
	s_add_i32 s44, s6, 1
	v_cndmask_b32_e32 v47, 0, v9, vcc
	v_cndmask_b32_e32 v46, v17, v8, vcc
	v_cndmask_b32_e32 v49, v12, v13, vcc
	v_cndmask_b32_e32 v48, v14, v15, vcc
	v_ashrrev_i32_e32 v17, 31, v16
	v_cmp_gt_i32_e32 vcc, s43, v8
	v_add_u32_e32 v54, 0xffffe008, v8
	v_add_u32_e32 v58, 0xffffe00c, v8
	v_add_u32_e32 v62, 0xffffe010, v8
	v_add_u32_e32 v66, 0xffffe014, v8
	v_add_u32_e32 v70, 0xffffe018, v8
	v_add_u32_e32 v74, 0xffffe01c, v8
	v_add_u32_e32 v78, 0xffffe020, v8
	v_add_u32_e32 v80, 0xffffe024, v8
	v_add_u32_e32 v84, 0xffffe028, v8
	v_add_u32_e32 v36, 44, v8
	v_add_u32_e32 v88, 0xffffe02c, v8
	v_add_u32_e32 v38, 48, v8
	v_add_u32_e32 v92, 0xffffe030, v8
	v_add_u32_e32 v40, 52, v8
	v_add_u32_e32 v98, 0xffffe034, v8
	v_add_u32_e32 v42, 56, v8
	v_add_u32_e32 v102, 0xffffe038, v8
	v_add_u32_e32 v44, 60, v8
	v_add_u32_e32 v106, 0xffffe03c, v8
	v_ashrrev_i32_e32 v19, 31, v18
	v_cmp_gt_i32_e64 s[6:7], s42, v18
	v_ashrrev_i32_e32 v21, 31, v20
	v_cmp_gt_i32_e64 s[8:9], s46, v8
	v_ashrrev_i32_e32 v23, 31, v22
	v_cmp_gt_i32_e64 s[10:11], s42, v22
	v_ashrrev_i32_e32 v25, 31, v24
	v_cmp_gt_i32_e64 s[12:13], s47, v8
	v_ashrrev_i32_e32 v27, 31, v26
	v_cmp_gt_i32_e64 s[14:15], s42, v26
	v_ashrrev_i32_e32 v29, 31, v28
	v_cmp_gt_i32_e64 s[16:17], s48, v8
	v_lshlrev_b64 v[50:51], 11, v[8:9]
	v_ashrrev_i32_e32 v31, 31, v30
	v_cmp_gt_i32_e64 s[18:19], s42, v30
	v_ashrrev_i32_e32 v33, 31, v32
	v_cmp_gt_i32_e64 s[20:21], s56, v8
	v_ashrrev_i32_e32 v35, 31, v34
	v_cmp_gt_i32_e64 s[22:23], s42, v34
	v_cmp_gt_i32_e64 s[24:25], s57, v8
	v_cmp_gt_i32_e64 s[28:29], s58, v8
	s_cmpk_gt_i32 s59, 0x7f
	v_lshlrev_b64 v[8:9], 12, v[46:47]
	v_cndmask_b32_e32 v47, 0, v17, vcc
	v_cndmask_b32_e32 v46, v52, v16, vcc
	v_ashrrev_i32_e32 v37, 31, v36
	v_ashrrev_i32_e32 v39, 31, v38
	v_cmp_gt_i32_e64 s[26:27], s42, v38
	v_ashrrev_i32_e32 v41, 31, v40
	v_ashrrev_i32_e32 v43, 31, v42
	v_cmp_gt_i32_e64 s[30:31], s42, v42
	v_ashrrev_i32_e32 v45, 31, v44
	v_cmp_gt_i32_e64 s[34:35], s42, v44
	v_cndmask_b32_e32 v53, v12, v13, vcc
	v_cndmask_b32_e32 v52, v14, v15, vcc
	v_cndmask_b32_e64 v55, 0, v19, s[6:7]
	v_cndmask_b32_e64 v54, v54, v18, s[6:7]
	v_cndmask_b32_e64 v57, v12, v13, s[6:7]
	v_cndmask_b32_e64 v56, v14, v15, s[6:7]
	v_cndmask_b32_e64 v59, 0, v21, s[8:9]
	v_cndmask_b32_e64 v58, v58, v20, s[8:9]
	v_cndmask_b32_e64 v63, 0, v23, s[10:11]
	v_cndmask_b32_e64 v62, v62, v22, s[10:11]
	v_cndmask_b32_e64 v67, 0, v25, s[12:13]
	v_cndmask_b32_e64 v66, v66, v24, s[12:13]
	v_cndmask_b32_e64 v71, 0, v27, s[14:15]
	v_cndmask_b32_e64 v70, v70, v26, s[14:15]
	v_cndmask_b32_e64 v75, 0, v29, s[16:17]
	v_cndmask_b32_e64 v74, v74, v28, s[16:17]
	v_lshl_add_u64 v[96:97], v[4:5], 0, v[50:51]
	v_lshlrev_b64 v[16:17], 11, v[16:17]
	v_cndmask_b32_e64 v51, 0, v31, s[18:19]
	v_cndmask_b32_e64 v50, v78, v30, s[18:19]
	v_cndmask_b32_e64 v81, 0, v33, s[20:21]
	v_cndmask_b32_e64 v80, v80, v32, s[20:21]
	v_cndmask_b32_e64 v85, 0, v35, s[22:23]
	v_cndmask_b32_e64 v84, v84, v34, s[22:23]
	v_lshlrev_b64 v[30:31], 11, v[30:31]
	v_lshlrev_b64 v[110:111], 11, v[32:33]
	v_lshlrev_b64 v[112:113], 11, v[34:35]
	s_cselect_b32 s6, s44, 0
	v_lshl_add_u64 v[32:33], v[48:49], 0, v[8:9]
	v_lshlrev_b64 v[34:35], 12, v[46:47]
	v_cndmask_b32_e64 v61, v12, v13, s[8:9]
	v_cndmask_b32_e64 v60, v14, v15, s[8:9]
	v_cndmask_b32_e64 v65, v12, v13, s[10:11]
	v_cndmask_b32_e64 v64, v14, v15, s[10:11]
	v_cndmask_b32_e64 v69, v12, v13, s[12:13]
	v_cndmask_b32_e64 v68, v14, v15, s[12:13]
	v_cndmask_b32_e64 v73, v12, v13, s[14:15]
	v_cndmask_b32_e64 v72, v14, v15, s[14:15]
	v_cndmask_b32_e64 v77, v12, v13, s[16:17]
	v_cndmask_b32_e64 v76, v14, v15, s[16:17]
	v_lshlrev_b64 v[18:19], 11, v[18:19]
	v_lshlrev_b64 v[20:21], 11, v[20:21]
	v_lshlrev_b64 v[22:23], 11, v[22:23]
	v_lshlrev_b64 v[24:25], 11, v[24:25]
	v_lshlrev_b64 v[26:27], 11, v[26:27]
	v_lshlrev_b64 v[28:29], 11, v[28:29]
	v_cndmask_b32_e64 v89, 0, v37, s[24:25]
	v_cndmask_b32_e64 v88, v88, v36, s[24:25]
	v_cndmask_b32_e64 v93, 0, v39, s[26:27]
	v_cndmask_b32_e64 v92, v92, v38, s[26:27]
	v_cndmask_b32_e64 v99, 0, v41, s[28:29]
	v_cndmask_b32_e64 v98, v98, v40, s[28:29]
	v_cndmask_b32_e64 v103, 0, v43, s[30:31]
	v_cndmask_b32_e64 v102, v102, v42, s[30:31]
	v_cndmask_b32_e64 v107, 0, v45, s[34:35]
	v_cndmask_b32_e64 v106, v106, v44, s[34:35]
	v_lshlrev_b64 v[114:115], 11, v[36:37]
	v_lshlrev_b64 v[116:117], 11, v[38:39]
	v_lshlrev_b64 v[118:119], 11, v[40:41]
	v_lshlrev_b64 v[120:121], 11, v[42:43]
	v_lshlrev_b64 v[122:123], 11, v[44:45]
	v_lshlrev_b64 v[36:37], 12, v[54:55]
	v_lshlrev_b64 v[38:39], 12, v[58:59]
	v_lshlrev_b64 v[40:41], 12, v[62:63]
	v_lshlrev_b64 v[42:43], 12, v[66:67]
	v_lshlrev_b64 v[44:45], 12, v[70:71]
	v_lshlrev_b64 v[46:47], 12, v[74:75]
	v_lshl_add_u64 v[124:125], v[4:5], 0, v[16:17]
	v_lshlrev_b64 v[16:17], 12, v[50:51]
	v_lshl_add_u64 v[8:9], v[4:5], 0, v[30:31]
	v_mad_u64_u32 v[50:51], s[6:7], s6, v11, v[6:7]
	v_lshl_add_u64 v[30:31], v[32:33], 0, v[2:3]
	v_lshl_add_u64 v[32:33], v[52:53], 0, v[34:35]
	v_cndmask_b32_e64 v79, v12, v13, s[18:19]
	v_cndmask_b32_e64 v78, v14, v15, s[18:19]
	v_cndmask_b32_e64 v83, v12, v13, s[20:21]
	v_cndmask_b32_e64 v82, v14, v15, s[20:21]
	v_cndmask_b32_e64 v87, v12, v13, s[22:23]
	v_cndmask_b32_e64 v86, v14, v15, s[22:23]
	v_cndmask_b32_e64 v91, v12, v13, s[24:25]
	v_cndmask_b32_e64 v90, v14, v15, s[24:25]
	v_cndmask_b32_e64 v95, v12, v13, s[26:27]
	v_cndmask_b32_e64 v94, v14, v15, s[26:27]
	v_cndmask_b32_e64 v101, v12, v13, s[28:29]
	v_cndmask_b32_e64 v100, v14, v15, s[28:29]
	v_cndmask_b32_e64 v105, v12, v13, s[30:31]
	v_cndmask_b32_e64 v104, v14, v15, s[30:31]
	v_cndmask_b32_e64 v109, v12, v13, s[34:35]
	v_cndmask_b32_e64 v108, v14, v15, s[34:35]
	v_lshl_add_u64 v[126:127], v[4:5], 0, v[18:19]
	v_lshl_add_u64 v[128:129], v[4:5], 0, v[20:21]
	v_lshl_add_u64 v[130:131], v[4:5], 0, v[22:23]
	v_lshl_add_u64 v[132:133], v[4:5], 0, v[24:25]
	v_lshl_add_u64 v[134:135], v[4:5], 0, v[26:27]
	v_lshl_add_u64 v[136:137], v[4:5], 0, v[28:29]
	v_lshlrev_b64 v[18:19], 12, v[80:81]
	v_lshlrev_b64 v[20:21], 12, v[84:85]
	v_lshlrev_b64 v[22:23], 12, v[88:89]
	v_lshlrev_b64 v[24:25], 12, v[92:93]
	v_lshlrev_b64 v[26:27], 12, v[98:99]
	v_lshlrev_b64 v[28:29], 12, v[102:103]
	v_lshlrev_b64 v[48:49], 12, v[106:107]
	v_lshl_add_u64 v[34:35], v[56:57], 0, v[36:37]
	v_lshl_add_u64 v[36:37], v[60:61], 0, v[38:39]
	v_lshl_add_u64 v[38:39], v[64:65], 0, v[40:41]
	v_lshl_add_u64 v[40:41], v[68:69], 0, v[42:43]
	v_lshl_add_u64 v[42:43], v[72:73], 0, v[44:45]
	v_lshl_add_u64 v[44:45], v[76:77], 0, v[46:47]
	v_lshl_add_u64 v[66:67], v[32:33], 0, v[2:3]
	v_add_co_u32_e32 v32, vcc, s49, v50
	v_lshl_add_u64 v[46:47], v[78:79], 0, v[16:17]
	v_lshl_add_u64 v[52:53], v[82:83], 0, v[18:19]
	v_lshl_add_u64 v[54:55], v[86:87], 0, v[20:21]
	v_lshl_add_u64 v[56:57], v[90:91], 0, v[22:23]
	v_lshl_add_u64 v[58:59], v[94:95], 0, v[24:25]
	v_lshl_add_u64 v[60:61], v[100:101], 0, v[26:27]
	v_lshl_add_u64 v[62:63], v[104:105], 0, v[28:29]
	v_lshl_add_u64 v[48:49], v[108:109], 0, v[48:49]
	v_lshl_add_u64 v[64:65], v[50:51], 0, s[38:39]
	global_load_dwordx4 v[16:19], v[30:31], off offset:16 nt
	global_load_dwordx4 v[20:23], v[30:31], off nt
	v_lshl_add_u64 v[68:69], v[34:35], 0, v[2:3]
	v_lshl_add_u64 v[70:71], v[36:37], 0, v[2:3]
	v_lshl_add_u64 v[72:73], v[38:39], 0, v[2:3]
	v_lshl_add_u64 v[76:77], v[40:41], 0, v[2:3]
	v_lshl_add_u64 v[84:85], v[42:43], 0, v[2:3]
	v_lshl_add_u64 v[92:93], v[44:45], 0, v[2:3]
	global_load_dwordx4 v[24:27], v[50:51], off offset:16 nt
	global_load_dwordx4 v[28:31], v[50:51], off nt
	v_addc_co_u32_e32 v33, vcc, 0, v51, vcc
	v_lshl_add_u64 v[98:99], v[46:47], 0, v[2:3]
	v_lshl_add_u64 v[100:101], v[52:53], 0, v[2:3]
	v_lshl_add_u64 v[102:103], v[54:55], 0, v[2:3]
	v_lshl_add_u64 v[104:105], v[56:57], 0, v[2:3]
	v_lshl_add_u64 v[106:107], v[58:59], 0, v[2:3]
	v_lshl_add_u64 v[108:109], v[60:61], 0, v[2:3]
	v_lshl_add_u64 v[138:139], v[62:63], 0, v[2:3]
	v_lshl_add_u64 v[140:141], v[48:49], 0, v[2:3]
	global_load_dwordx4 v[32:35], v[32:33], off nt
	s_nop 0
	global_load_dwordx4 v[36:39], v[64:65], off offset:16 nt
	global_load_dwordx4 v[40:43], v[66:67], off nt
	global_load_dwordx4 v[44:47], v[66:67], off offset:16 nt
	global_load_dwordx4 v[48:51], v[68:69], off nt
	global_load_dwordx4 v[52:55], v[68:69], off offset:16 nt
	global_load_dwordx4 v[56:59], v[70:71], off nt
	global_load_dwordx4 v[60:63], v[70:71], off offset:16 nt
	s_nop 0
	global_load_dwordx4 v[64:67], v[72:73], off nt
	global_load_dwordx4 v[68:71], v[72:73], off offset:16 nt
	s_nop 0
	global_load_dwordx4 v[72:75], v[76:77], off nt
	s_nop 0
	global_load_dwordx4 v[76:79], v[76:77], off offset:16 nt
	s_nop 0
	global_load_dwordx4 v[80:83], v[84:85], off nt
	s_nop 0
	global_load_dwordx4 v[84:87], v[84:85], off offset:16 nt
	s_nop 0
	global_load_dwordx4 v[88:91], v[92:93], off nt
	s_nop 0
	global_load_dwordx4 v[92:95], v[92:93], off offset:16 nt
	s_add_i32 s59, s59, s70
	s_add_i32 s41, s41, s40
	v_add_u32_e32 v10, s40, v10
	s_cmpk_lt_i32 s59, 0x100
	s_waitcnt vmcnt(15)
	v_pk_add_f32 v[142:143], v[32:33], 1.0 op_sel_hi:[1,0]
	v_pk_add_f32 v[144:145], v[34:35], 1.0 op_sel_hi:[1,0]
	s_waitcnt vmcnt(14)
	v_pk_add_f32 v[146:147], v[36:37], 1.0 op_sel_hi:[1,0]
	v_pk_add_f32 v[148:149], v[38:39], 1.0 op_sel_hi:[1,0]
	v_pk_fma_f32 v[20:21], v[142:143], v[20:21], v[28:29]
	v_pk_fma_f32 v[22:23], v[144:145], v[22:23], v[30:31]
	v_pk_fma_f32 v[32:33], v[146:147], v[16:17], v[24:25]
	v_pk_fma_f32 v[34:35], v[148:149], v[18:19], v[26:27]
	s_waitcnt vmcnt(13)
	v_pk_fma_f32 v[36:37], v[142:143], v[40:41], v[28:29]
	v_pk_fma_f32 v[38:39], v[144:145], v[42:43], v[30:31]
	s_waitcnt vmcnt(12)
	v_pk_fma_f32 v[40:41], v[146:147], v[44:45], v[24:25]
	v_pk_fma_f32 v[42:43], v[148:149], v[46:47], v[26:27]
	s_waitcnt vmcnt(11)
	v_pk_fma_f32 v[44:45], v[142:143], v[48:49], v[28:29]
	v_pk_fma_f32 v[46:47], v[144:145], v[50:51], v[30:31]
	s_waitcnt vmcnt(10)
	v_pk_fma_f32 v[48:49], v[146:147], v[52:53], v[24:25]
	v_pk_fma_f32 v[50:51], v[148:149], v[54:55], v[26:27]
	s_waitcnt vmcnt(9)
	v_pk_fma_f32 v[52:53], v[142:143], v[56:57], v[28:29]
	v_pk_fma_f32 v[54:55], v[144:145], v[58:59], v[30:31]
	s_waitcnt vmcnt(8)
	v_pk_fma_f32 v[56:57], v[146:147], v[60:61], v[24:25]
	v_pk_fma_f32 v[58:59], v[148:149], v[62:63], v[26:27]
	s_waitcnt vmcnt(7)
	v_pk_fma_f32 v[60:61], v[142:143], v[64:65], v[28:29]
	v_pk_fma_f32 v[62:63], v[144:145], v[66:67], v[30:31]
	s_waitcnt vmcnt(6)
	v_pk_fma_f32 v[64:65], v[146:147], v[68:69], v[24:25]
	v_pk_fma_f32 v[66:67], v[148:149], v[70:71], v[26:27]
	s_waitcnt vmcnt(5)
	v_pk_fma_f32 v[68:69], v[142:143], v[72:73], v[28:29]
	v_pk_fma_f32 v[70:71], v[144:145], v[74:75], v[30:31]
	s_waitcnt vmcnt(4)
	v_pk_fma_f32 v[72:73], v[146:147], v[76:77], v[24:25]
	v_pk_fma_f32 v[74:75], v[148:149], v[78:79], v[26:27]
	s_waitcnt vmcnt(3)
	v_pk_fma_f32 v[76:77], v[142:143], v[80:81], v[28:29]
	v_pk_fma_f32 v[78:79], v[144:145], v[82:83], v[30:31]
	s_waitcnt vmcnt(2)
	v_pk_fma_f32 v[80:81], v[146:147], v[84:85], v[24:25]
	v_pk_fma_f32 v[82:83], v[148:149], v[86:87], v[26:27]
	s_waitcnt vmcnt(1)
	v_pk_fma_f32 v[84:85], v[142:143], v[88:89], v[28:29]
	v_pk_fma_f32 v[86:87], v[144:145], v[90:91], v[30:31]
	s_waitcnt vmcnt(0)
	v_pk_fma_f32 v[88:89], v[146:147], v[92:93], v[24:25]
	v_pk_fma_f32 v[90:91], v[148:149], v[94:95], v[26:27]
	v_cvt_pk_bf16_f32 v16, v20, v21
	v_cvt_pk_bf16_f32 v17, v22, v23
	v_cvt_pk_bf16_f32 v18, v32, v33
	v_cvt_pk_bf16_f32 v19, v34, v35
	v_cvt_pk_bf16_f32 v20, v36, v37
	v_cvt_pk_bf16_f32 v21, v38, v39
	v_cvt_pk_bf16_f32 v22, v40, v41
	v_cvt_pk_bf16_f32 v23, v42, v43
	v_cvt_pk_bf16_f32 v32, v44, v45
	v_cvt_pk_bf16_f32 v33, v46, v47
	v_cvt_pk_bf16_f32 v34, v48, v49
	v_cvt_pk_bf16_f32 v35, v50, v51
	v_cvt_pk_bf16_f32 v36, v52, v53
	v_cvt_pk_bf16_f32 v37, v54, v55
	v_cvt_pk_bf16_f32 v38, v56, v57
	v_cvt_pk_bf16_f32 v39, v58, v59
	v_cvt_pk_bf16_f32 v40, v60, v61
	v_cvt_pk_bf16_f32 v41, v62, v63
	v_cvt_pk_bf16_f32 v42, v64, v65
	v_cvt_pk_bf16_f32 v43, v66, v67
	v_cvt_pk_bf16_f32 v44, v68, v69
	v_cvt_pk_bf16_f32 v45, v70, v71
	v_cvt_pk_bf16_f32 v46, v72, v73
	v_cvt_pk_bf16_f32 v47, v74, v75
	v_cvt_pk_bf16_f32 v48, v76, v77
	v_cvt_pk_bf16_f32 v49, v78, v79
	v_cvt_pk_bf16_f32 v50, v80, v81
	v_cvt_pk_bf16_f32 v51, v82, v83
	v_cvt_pk_bf16_f32 v52, v84, v85
	v_cvt_pk_bf16_f32 v53, v86, v87
	v_cvt_pk_bf16_f32 v54, v88, v89
	v_cvt_pk_bf16_f32 v55, v90, v91
	global_store_dwordx4 v[96:97], v[16:19], off
	global_store_dwordx4 v[124:125], v[20:23], off
	global_store_dwordx4 v[126:127], v[32:35], off
	global_store_dwordx4 v[128:129], v[36:39], off
	global_store_dwordx4 v[130:131], v[40:43], off
	global_store_dwordx4 v[132:133], v[44:47], off
	global_store_dwordx4 v[134:135], v[48:51], off
	global_store_dwordx4 v[136:137], v[52:55], off
	global_load_dwordx4 v[16:19], v[98:99], off nt
	global_load_dwordx4 v[20:23], v[98:99], off offset:16 nt
	global_load_dwordx4 v[32:35], v[100:101], off nt
	global_load_dwordx4 v[36:39], v[100:101], off offset:16 nt
	global_load_dwordx4 v[40:43], v[102:103], off nt
	global_load_dwordx4 v[44:47], v[102:103], off offset:16 nt
	global_load_dwordx4 v[48:51], v[104:105], off nt
	global_load_dwordx4 v[52:55], v[104:105], off offset:16 nt
	global_load_dwordx4 v[56:59], v[106:107], off nt
	global_load_dwordx4 v[60:63], v[106:107], off offset:16 nt
	global_load_dwordx4 v[64:67], v[108:109], off nt
	global_load_dwordx4 v[68:71], v[108:109], off offset:16 nt
	global_load_dwordx4 v[72:75], v[138:139], off nt
	global_load_dwordx4 v[76:79], v[138:139], off offset:16 nt
	global_load_dwordx4 v[80:83], v[140:141], off nt
	global_load_dwordx4 v[84:87], v[140:141], off offset:16 nt
	v_lshl_add_u64 v[88:89], v[4:5], 0, v[110:111]
	v_lshl_add_u64 v[90:91], v[4:5], 0, v[112:113]
	v_lshl_add_u64 v[92:93], v[4:5], 0, v[114:115]
	v_lshl_add_u64 v[94:95], v[4:5], 0, v[116:117]
	v_lshl_add_u64 v[96:97], v[4:5], 0, v[118:119]
	v_lshl_add_u64 v[98:99], v[4:5], 0, v[120:121]
	v_lshl_add_u64 v[100:101], v[4:5], 0, v[122:123]
	s_waitcnt vmcnt(15)
	v_pk_fma_f32 v[16:17], v[142:143], v[16:17], v[28:29]
	v_pk_fma_f32 v[18:19], v[144:145], v[18:19], v[30:31]
	s_waitcnt vmcnt(14)
	v_pk_fma_f32 v[20:21], v[146:147], v[20:21], v[24:25]
	v_pk_fma_f32 v[22:23], v[148:149], v[22:23], v[26:27]
	s_waitcnt vmcnt(13)
	v_pk_fma_f32 v[32:33], v[142:143], v[32:33], v[28:29]
	v_pk_fma_f32 v[34:35], v[144:145], v[34:35], v[30:31]
	s_waitcnt vmcnt(12)
	v_pk_fma_f32 v[36:37], v[146:147], v[36:37], v[24:25]
	v_pk_fma_f32 v[38:39], v[148:149], v[38:39], v[26:27]
	s_waitcnt vmcnt(11)
	v_pk_fma_f32 v[40:41], v[142:143], v[40:41], v[28:29]
	v_pk_fma_f32 v[42:43], v[144:145], v[42:43], v[30:31]
	s_waitcnt vmcnt(10)
	v_pk_fma_f32 v[44:45], v[146:147], v[44:45], v[24:25]
	v_pk_fma_f32 v[46:47], v[148:149], v[46:47], v[26:27]
	s_waitcnt vmcnt(9)
	v_pk_fma_f32 v[48:49], v[142:143], v[48:49], v[28:29]
	v_pk_fma_f32 v[50:51], v[144:145], v[50:51], v[30:31]
	s_waitcnt vmcnt(8)
	v_pk_fma_f32 v[52:53], v[146:147], v[52:53], v[24:25]
	v_pk_fma_f32 v[54:55], v[148:149], v[54:55], v[26:27]
	s_waitcnt vmcnt(7)
	v_pk_fma_f32 v[56:57], v[142:143], v[56:57], v[28:29]
	v_pk_fma_f32 v[58:59], v[144:145], v[58:59], v[30:31]
	s_waitcnt vmcnt(6)
	v_pk_fma_f32 v[60:61], v[146:147], v[60:61], v[24:25]
	v_pk_fma_f32 v[62:63], v[148:149], v[62:63], v[26:27]
	s_waitcnt vmcnt(5)
	v_pk_fma_f32 v[64:65], v[142:143], v[64:65], v[28:29]
	v_pk_fma_f32 v[66:67], v[144:145], v[66:67], v[30:31]
	s_waitcnt vmcnt(4)
	v_pk_fma_f32 v[68:69], v[146:147], v[68:69], v[24:25]
	v_pk_fma_f32 v[70:71], v[148:149], v[70:71], v[26:27]
	s_waitcnt vmcnt(3)
	v_pk_fma_f32 v[72:73], v[142:143], v[72:73], v[28:29]
	v_pk_fma_f32 v[74:75], v[144:145], v[74:75], v[30:31]
	s_waitcnt vmcnt(2)
	v_pk_fma_f32 v[76:77], v[146:147], v[76:77], v[24:25]
	v_pk_fma_f32 v[78:79], v[148:149], v[78:79], v[26:27]
	s_waitcnt vmcnt(1)
	v_pk_fma_f32 v[80:81], v[142:143], v[80:81], v[28:29]
	v_pk_fma_f32 v[82:83], v[144:145], v[82:83], v[30:31]
	s_waitcnt vmcnt(0)
	v_pk_fma_f32 v[84:85], v[146:147], v[84:85], v[24:25]
	v_pk_fma_f32 v[86:87], v[148:149], v[86:87], v[26:27]
	v_cvt_pk_bf16_f32 v16, v16, v17
	v_cvt_pk_bf16_f32 v17, v18, v19
	v_cvt_pk_bf16_f32 v18, v20, v21
	v_cvt_pk_bf16_f32 v19, v22, v23
	v_cvt_pk_bf16_f32 v20, v32, v33
	v_cvt_pk_bf16_f32 v21, v34, v35
	v_cvt_pk_bf16_f32 v22, v36, v37
	v_cvt_pk_bf16_f32 v23, v38, v39
	v_cvt_pk_bf16_f32 v24, v40, v41
	v_cvt_pk_bf16_f32 v25, v42, v43
	v_cvt_pk_bf16_f32 v26, v44, v45
	v_cvt_pk_bf16_f32 v27, v46, v47
	v_cvt_pk_bf16_f32 v28, v48, v49
	v_cvt_pk_bf16_f32 v29, v50, v51
	v_cvt_pk_bf16_f32 v30, v52, v53
	v_cvt_pk_bf16_f32 v31, v54, v55
	v_cvt_pk_bf16_f32 v32, v56, v57
	v_cvt_pk_bf16_f32 v33, v58, v59
	v_cvt_pk_bf16_f32 v34, v60, v61
	v_cvt_pk_bf16_f32 v35, v62, v63
	v_cvt_pk_bf16_f32 v36, v64, v65
	v_cvt_pk_bf16_f32 v37, v66, v67
	v_cvt_pk_bf16_f32 v38, v68, v69
	v_cvt_pk_bf16_f32 v39, v70, v71
	v_cvt_pk_bf16_f32 v40, v72, v73
	v_cvt_pk_bf16_f32 v41, v74, v75
	v_cvt_pk_bf16_f32 v42, v76, v77
	v_cvt_pk_bf16_f32 v43, v78, v79
	v_cvt_pk_bf16_f32 v44, v80, v81
	v_cvt_pk_bf16_f32 v45, v82, v83
	v_cvt_pk_bf16_f32 v46, v84, v85
	v_cvt_pk_bf16_f32 v47, v86, v87
	global_store_dwordx4 v[8:9], v[16:19], off
	global_store_dwordx4 v[88:89], v[20:23], off
	global_store_dwordx4 v[90:91], v[24:27], off
	global_store_dwordx4 v[92:93], v[28:31], off
	global_store_dwordx4 v[94:95], v[32:35], off
	global_store_dwordx4 v[96:97], v[36:39], off
	global_store_dwordx4 v[98:99], v[40:43], off
	global_store_dwordx4 v[100:101], v[44:47], off
	s_cbranch_scc1 .LBB0_139
